# scan RMS row sums via DPP row ops instead of 16 ds_bpermute per chunk (on top of prep batching + K-loop peel)
# baseline (speedup 1.0000x reference)
; #define LAS __attribute__((address_space(3)))
; __device__ __forceinline__ void strip_mm(f32x4 (&acc)[4], const LAS unsigned char* A, const LAS unsigned char* Bt, const int r0, const int lane) {
;     const int c16 = lane & 15, q4 = lane >> 4; bf16x8 a[2], b[2][4];
; #pragma unroll
;     for (int ks = 0; ks < 2; ++ks) { a[ks] = *(const LAS bf16x8*)(A + (r0 + c16) * STRB + (32 * ks + 8 * q4) * 2);
; #pragma unroll
;         for (int tn = 0; tn < 4; ++tn) b[ks][tn] = *(const LAS bf16x8*)(Bt + (16 * tn + c16) * STRB + (32 * ks + 8 * q4) * 2); }
;     __builtin_amdgcn_sched_barrier(0);
; #pragma unroll
;     for (int ks = 0; ks < 2; ++ks)
; #pragma unroll
;         for (int tn = 0; tn < 4; ++tn) acc[tn] = __builtin_amdgcn_mfma_f32_16x16x32_bf16(a[ks], b[ks][tn], acc[tn], 0, 0, 0);
; }
.LBB0_1168:
	s_waitcnt lgkmcnt(0)
	s_barrier
	s_mov_b64 s[0:1], -1
	s_and_b64 vcc, exec, s[6:7]
	v_mbcnt_hi_u32_b32 v145, -1, v120
	s_cbranch_vccz .LBB0_1170
	ds_read_b128 v[146:149], v137
	ds_read_b128 v[150:153], v137 offset:2304
	ds_read_b128 v[154:157], v137 offset:4608
	ds_read_b128 v[158:161], v137 offset:6912
	ds_read_b128 v[162:165], v132 offset:9216
	ds_read_b128 v[166:169], v132 offset:9280
	ds_read_b128 v[170:173], v138 offset:64
	ds_read_b128 v[174:177], v139 offset:2304
	ds_read_b128 v[178:181], v139 offset:4608
	ds_read_b128 v[182:185], v139 offset:6912
	s_waitcnt lgkmcnt(5)
	v_mfma_f32_16x16x32_bf16 v[72:75], v[162:165], v[146:149], v[72:75]
	v_and_b32_e32 v117, 64, v145
	v_xor_b32_e32 v116, 1, v145
	v_mfma_f32_16x16x32_bf16 v[76:79], v[162:165], v[150:153], v[76:79]
	v_mfma_f32_16x16x32_bf16 v[80:83], v[162:165], v[154:157], v[80:83]
	v_add_u32_e32 v154, 64, v117
	v_cmp_lt_i32_e32 vcc, v116, v154
	v_mfma_f32_16x16x32_bf16 v[84:87], v[162:165], v[158:161], v[84:87]
	s_nop 0
	v_cndmask_b32_e32 v116, v145, v116, vcc
	v_lshlrev_b32_e32 v158, 2, v116
	s_waitcnt lgkmcnt(3)
	v_mfma_f32_16x16x32_bf16 v[72:75], v[166:169], v[170:173], v[72:75]
	s_waitcnt lgkmcnt(2)
	v_mfma_f32_16x16x32_bf16 v[76:79], v[166:169], v[174:177], v[76:79]
	s_waitcnt lgkmcnt(0)
	v_mfma_f32_16x16x32_bf16 v[84:87], v[166:169], v[182:185], v[84:87]
	v_mfma_f32_16x16x32_bf16 v[80:83], v[166:169], v[178:181], v[80:83]
	s_nop 7
	s_nop 1
	v_mul_f32_e32 v146, v72, v72
	v_mul_f32_e32 v147, v73, v73
	v_mul_f32_e32 v148, v74, v74
	v_mul_f32_e32 v149, v75, v75
	v_mul_f32_e32 v150, v76, v76
	v_mul_f32_e32 v151, v77, v77
	v_mul_f32_e32 v152, v78, v78
	v_mul_f32_e32 v153, v79, v79
	v_add_f32_e32 v146, v146, v150
	v_add_f32_e32 v147, v147, v151
	v_add_f32_e32 v148, v148, v152
	v_add_f32_e32 v149, v149, v153
	v_mul_f32_e32 v150, v80, v80
	v_mul_f32_e32 v151, v81, v81
	v_mul_f32_e32 v152, v82, v82
	v_mul_f32_e32 v153, v83, v83
	v_add_f32_e32 v146, v146, v150
	v_add_f32_e32 v147, v147, v151
	v_add_f32_e32 v148, v148, v152
	v_add_f32_e32 v149, v149, v153
	v_mul_f32_e32 v150, v84, v84
	v_mul_f32_e32 v151, v85, v85
	v_mul_f32_e32 v152, v86, v86
	v_mul_f32_e32 v153, v87, v87
	v_add_f32_e32 v146, v146, v150
	v_add_f32_e32 v147, v147, v151
	v_add_f32_e32 v148, v148, v152
	v_add_f32_e32 v149, v149, v153
	v_add_f32_dpp v146, v146, v146 quad_perm:[1,0,3,2] row_mask:0xf bank_mask:0xf
	v_add_f32_dpp v147, v147, v147 quad_perm:[1,0,3,2] row_mask:0xf bank_mask:0xf
	v_add_f32_dpp v148, v148, v148 quad_perm:[1,0,3,2] row_mask:0xf bank_mask:0xf
	v_add_f32_dpp v149, v149, v149 quad_perm:[1,0,3,2] row_mask:0xf bank_mask:0xf
	v_add_f32_dpp v146, v146, v146 quad_perm:[2,3,0,1] row_mask:0xf bank_mask:0xf
	v_add_f32_dpp v147, v147, v147 quad_perm:[2,3,0,1] row_mask:0xf bank_mask:0xf
	v_add_f32_dpp v148, v148, v148 quad_perm:[2,3,0,1] row_mask:0xf bank_mask:0xf
	v_add_f32_dpp v149, v149, v149 quad_perm:[2,3,0,1] row_mask:0xf bank_mask:0xf
	v_add_f32_dpp v146, v146, v146 row_half_mirror row_mask:0xf bank_mask:0xf
	v_add_f32_dpp v147, v147, v147 row_half_mirror row_mask:0xf bank_mask:0xf
	v_add_f32_dpp v148, v148, v148 row_half_mirror row_mask:0xf bank_mask:0xf
	v_add_f32_dpp v149, v149, v149 row_half_mirror row_mask:0xf bank_mask:0xf
	v_add_f32_dpp v146, v146, v146 row_mirror row_mask:0xf bank_mask:0xf
	v_add_f32_dpp v147, v147, v147 row_mirror row_mask:0xf bank_mask:0xf
	v_add_f32_dpp v148, v148, v148 row_mirror row_mask:0xf bank_mask:0xf
	v_add_f32_dpp v149, v149, v149 row_mirror row_mask:0xf bank_mask:0xf
	v_mov_b32_e32 v158, s40
	s_nop 0
	v_fma_f32 v146, v146, s38, v158
	v_fma_f32 v147, v147, s38, v158
	v_fma_f32 v148, v148, s38, v158
	v_fma_f32 v149, v149, s38, v158
	v_cmp_gt_f32_e32 vcc, s74, v146
	v_mul_f32_e32 v150, 0x4b800000, v146
	s_nop 0
	v_cndmask_b32_e32 v146, v146, v150, vcc
	v_rsq_f32_e32 v146, v146
	s_nop 0
	v_mul_f32_e32 v150, 0x45800000, v146
	v_cndmask_b32_e32 v146, v146, v150, vcc
	v_cmp_gt_f32_e32 vcc, s74, v147
	v_mul_f32_e32 v151, 0x4b800000, v147
	s_nop 0
	v_cndmask_b32_e32 v147, v147, v151, vcc
	v_rsq_f32_e32 v147, v147
	s_nop 0
	v_mul_f32_e32 v151, 0x45800000, v147
	v_cndmask_b32_e32 v147, v147, v151, vcc
	v_cmp_gt_f32_e32 vcc, s74, v148
	v_mul_f32_e32 v152, 0x4b800000, v148
	s_nop 0
	v_cndmask_b32_e32 v148, v148, v152, vcc
	v_rsq_f32_e32 v148, v148
	s_nop 0
	v_mul_f32_e32 v152, 0x45800000, v148
	v_cndmask_b32_e32 v148, v148, v152, vcc
	v_cmp_gt_f32_e32 vcc, s74, v149
	v_mul_f32_e32 v153, 0x4b800000, v149
	s_nop 0
	v_cndmask_b32_e32 v149, v149, v153, vcc
	v_rsq_f32_e32 v149, v149
	s_nop 0
	v_mul_f32_e32 v153, 0x45800000, v149
	v_cndmask_b32_e32 v149, v149, v153, vcc
	v_mul_f32_e32 v154, v72, v146
	v_cvt_pk_bf16_f32 v154, v154, s0
	ds_write_b16 v140, v154
	v_mul_f32_e32 v155, v76, v146
	v_cvt_pk_bf16_f32 v155, v155, s0
	ds_write_b16 v140, v155 offset:32
	v_mul_f32_e32 v156, v80, v146
	v_cvt_pk_bf16_f32 v156, v156, s0
	ds_write_b16 v140, v156 offset:64
	v_mul_f32_e32 v157, v84, v146
	v_cvt_pk_bf16_f32 v157, v157, s0
	ds_write_b16 v140, v157 offset:96
	v_mul_f32_e32 v154, v73, v147
	v_cvt_pk_bf16_f32 v154, v154, s0
	ds_write_b16 v140, v154 offset:144
	v_mul_f32_e32 v155, v77, v147
	v_cvt_pk_bf16_f32 v155, v155, s0
	ds_write_b16 v140, v155 offset:176
	v_mul_f32_e32 v156, v81, v147
	v_cvt_pk_bf16_f32 v156, v156, s0
	ds_write_b16 v140, v156 offset:208
	v_mul_f32_e32 v157, v85, v147
	v_cvt_pk_bf16_f32 v157, v157, s0
	ds_write_b16 v140, v157 offset:240
	v_mul_f32_e32 v154, v74, v148
	v_cvt_pk_bf16_f32 v154, v154, s0
	ds_write_b16 v140, v154 offset:288
	v_mul_f32_e32 v155, v78, v148
	v_cvt_pk_bf16_f32 v155, v155, s0
	ds_write_b16 v140, v155 offset:320
	v_mul_f32_e32 v156, v82, v148
	v_cvt_pk_bf16_f32 v156, v156, s0
	ds_write_b16 v140, v156 offset:352
	v_mul_f32_e32 v157, v86, v148
	v_cvt_pk_bf16_f32 v157, v157, s0
	ds_write_b16 v140, v157 offset:384
	v_mul_f32_e32 v154, v75, v149
	v_cvt_pk_bf16_f32 v154, v154, s0
	ds_write_b16 v140, v154 offset:432
	v_mul_f32_e32 v155, v79, v149
	v_cvt_pk_bf16_f32 v155, v155, s0
	ds_write_b16 v140, v155 offset:464
	v_mul_f32_e32 v156, v83, v149
	v_cvt_pk_bf16_f32 v156, v156, s0
	ds_write_b16 v140, v156 offset:496
	v_mul_f32_e32 v157, v87, v149
	v_cvt_pk_bf16_f32 v157, v157, s0
	ds_write_b16 v140, v157 offset:528
	s_mov_b64 s[0:1], 0

; #define LAS __attribute__((address_space(3)))
; __device__ __forceinline__ void strip_mm(f32x4 (&acc)[4], const LAS unsigned char* A, const LAS unsigned char* Bt, const int r0, const int lane) {
;     const int c16 = lane & 15, q4 = lane >> 4; bf16x8 a[2], b[2][4];
; #pragma unroll
;     for (int ks = 0; ks < 2; ++ks) { a[ks] = *(const LAS bf16x8*)(A + (r0 + c16) * STRB + (32 * ks + 8 * q4) * 2);
; #pragma unroll
;         for (int tn = 0; tn < 4; ++tn) b[ks][tn] = *(const LAS bf16x8*)(Bt + (16 * tn + c16) * STRB + (32 * ks + 8 * q4) * 2); }
;     __builtin_amdgcn_sched_barrier(0);
; #pragma unroll
;     for (int ks = 0; ks < 2; ++ks)
; #pragma unroll
;         for (int tn = 0; tn < 4; ++tn) acc[tn] = __builtin_amdgcn_mfma_f32_16x16x32_bf16(a[ks], b[ks][tn], acc[tn], 0, 0, 0);
; }
.LBB0_1180:
	s_waitcnt lgkmcnt(0)
	s_barrier
	s_mov_b64 s[56:57], -1
	s_and_b64 vcc, exec, s[6:7]
	s_cbranch_vccz .LBB0_1183
	ds_read_b128 v[146:149], v137
	ds_read_b128 v[150:153], v137 offset:2304
	ds_read_b128 v[154:157], v137 offset:4608
	ds_read_b128 v[158:161], v137 offset:6912
	ds_read_b128 v[162:165], v132 offset:55296
	ds_read_b128 v[166:169], v132 offset:55360
	ds_read_b128 v[170:173], v138 offset:64
	ds_read_b128 v[174:177], v139 offset:2304
	ds_read_b128 v[178:181], v139 offset:4608
	ds_read_b128 v[182:185], v139 offset:6912
	s_waitcnt lgkmcnt(5)
	v_mfma_f32_16x16x32_bf16 v[72:75], v[162:165], v[146:149], v[72:75]
	v_and_b32_e32 v115, 64, v145
	v_xor_b32_e32 v114, 1, v145
	v_mfma_f32_16x16x32_bf16 v[76:79], v[162:165], v[150:153], v[76:79]
	v_mfma_f32_16x16x32_bf16 v[80:83], v[162:165], v[154:157], v[80:83]
	v_add_u32_e32 v154, 64, v115
	v_cmp_lt_i32_e32 vcc, v114, v154
	v_mfma_f32_16x16x32_bf16 v[84:87], v[162:165], v[158:161], v[84:87]
	s_nop 0
	v_cndmask_b32_e32 v114, v145, v114, vcc
	v_lshlrev_b32_e32 v158, 2, v114
	s_waitcnt lgkmcnt(3)
	v_mfma_f32_16x16x32_bf16 v[72:75], v[166:169], v[170:173], v[72:75]
	s_waitcnt lgkmcnt(2)
	v_mfma_f32_16x16x32_bf16 v[76:79], v[166:169], v[174:177], v[76:79]
	s_waitcnt lgkmcnt(0)
	v_mfma_f32_16x16x32_bf16 v[84:87], v[166:169], v[182:185], v[84:87]
	v_mfma_f32_16x16x32_bf16 v[80:83], v[166:169], v[178:181], v[80:83]
	s_nop 7
	s_nop 1
	v_mul_f32_e32 v146, v72, v72
	v_mul_f32_e32 v147, v73, v73
	v_mul_f32_e32 v148, v74, v74
	v_mul_f32_e32 v149, v75, v75
	v_mul_f32_e32 v150, v76, v76
	v_mul_f32_e32 v151, v77, v77
	v_mul_f32_e32 v152, v78, v78
	v_mul_f32_e32 v153, v79, v79
	v_add_f32_e32 v146, v146, v150
	v_add_f32_e32 v147, v147, v151
	v_add_f32_e32 v148, v148, v152
	v_add_f32_e32 v149, v149, v153
	v_mul_f32_e32 v150, v80, v80
	v_mul_f32_e32 v151, v81, v81
	v_mul_f32_e32 v152, v82, v82
	v_mul_f32_e32 v153, v83, v83
	v_add_f32_e32 v146, v146, v150
	v_add_f32_e32 v147, v147, v151
	v_add_f32_e32 v148, v148, v152
	v_add_f32_e32 v149, v149, v153
	v_mul_f32_e32 v150, v84, v84
	v_mul_f32_e32 v151, v85, v85
	v_mul_f32_e32 v152, v86, v86
	v_mul_f32_e32 v153, v87, v87
	v_add_f32_e32 v146, v146, v150
	v_add_f32_e32 v147, v147, v151
	v_add_f32_e32 v148, v148, v152
	v_add_f32_e32 v149, v149, v153
	v_add_f32_dpp v146, v146, v146 quad_perm:[1,0,3,2] row_mask:0xf bank_mask:0xf
	v_add_f32_dpp v147, v147, v147 quad_perm:[1,0,3,2] row_mask:0xf bank_mask:0xf
	v_add_f32_dpp v148, v148, v148 quad_perm:[1,0,3,2] row_mask:0xf bank_mask:0xf
	v_add_f32_dpp v149, v149, v149 quad_perm:[1,0,3,2] row_mask:0xf bank_mask:0xf
	v_add_f32_dpp v146, v146, v146 quad_perm:[2,3,0,1] row_mask:0xf bank_mask:0xf
	v_add_f32_dpp v147, v147, v147 quad_perm:[2,3,0,1] row_mask:0xf bank_mask:0xf
	v_add_f32_dpp v148, v148, v148 quad_perm:[2,3,0,1] row_mask:0xf bank_mask:0xf
	v_add_f32_dpp v149, v149, v149 quad_perm:[2,3,0,1] row_mask:0xf bank_mask:0xf
	v_add_f32_dpp v146, v146, v146 row_half_mirror row_mask:0xf bank_mask:0xf
	v_add_f32_dpp v147, v147, v147 row_half_mirror row_mask:0xf bank_mask:0xf
	v_add_f32_dpp v148, v148, v148 row_half_mirror row_mask:0xf bank_mask:0xf
	v_add_f32_dpp v149, v149, v149 row_half_mirror row_mask:0xf bank_mask:0xf
	v_add_f32_dpp v146, v146, v146 row_mirror row_mask:0xf bank_mask:0xf
	v_add_f32_dpp v147, v147, v147 row_mirror row_mask:0xf bank_mask:0xf
	v_add_f32_dpp v148, v148, v148 row_mirror row_mask:0xf bank_mask:0xf
	v_add_f32_dpp v149, v149, v149 row_mirror row_mask:0xf bank_mask:0xf
	v_mov_b32_e32 v158, s40
	s_nop 0
	v_fma_f32 v146, v146, s38, v158
	v_fma_f32 v147, v147, s38, v158
	v_fma_f32 v148, v148, s38, v158
	v_fma_f32 v149, v149, s38, v158
	v_cmp_gt_f32_e32 vcc, s74, v146
	v_mul_f32_e32 v150, 0x4b800000, v146
	s_nop 0
	v_cndmask_b32_e32 v146, v146, v150, vcc
	v_rsq_f32_e32 v146, v146
	s_nop 0
	v_mul_f32_e32 v150, 0x45800000, v146
	v_cndmask_b32_e32 v146, v146, v150, vcc
	v_cmp_gt_f32_e32 vcc, s74, v147
	v_mul_f32_e32 v151, 0x4b800000, v147
	s_nop 0
	v_cndmask_b32_e32 v147, v147, v151, vcc
	v_rsq_f32_e32 v147, v147
	s_nop 0
	v_mul_f32_e32 v151, 0x45800000, v147
	v_cndmask_b32_e32 v147, v147, v151, vcc
	v_cmp_gt_f32_e32 vcc, s74, v148
	v_mul_f32_e32 v152, 0x4b800000, v148
	s_nop 0
	v_cndmask_b32_e32 v148, v148, v152, vcc
	v_rsq_f32_e32 v148, v148
	s_nop 0
	v_mul_f32_e32 v152, 0x45800000, v148
	v_cndmask_b32_e32 v148, v148, v152, vcc
	v_cmp_gt_f32_e32 vcc, s74, v149
	v_mul_f32_e32 v153, 0x4b800000, v149
	s_nop 0
	v_cndmask_b32_e32 v149, v149, v153, vcc
	v_rsq_f32_e32 v149, v149
	s_nop 0
	v_mul_f32_e32 v153, 0x45800000, v149
	v_cndmask_b32_e32 v149, v149, v153, vcc
	v_mul_f32_e32 v154, v72, v146
	v_cvt_pk_bf16_f32 v154, v154, s0
	ds_write_b16 v140, v154
	v_mul_f32_e32 v155, v76, v146
	v_cvt_pk_bf16_f32 v155, v155, s0
	ds_write_b16 v140, v155 offset:32
	v_mul_f32_e32 v156, v80, v146
	v_cvt_pk_bf16_f32 v156, v156, s0
	ds_write_b16 v140, v156 offset:64
	v_mul_f32_e32 v157, v84, v146
	v_cvt_pk_bf16_f32 v157, v157, s0
	ds_write_b16 v140, v157 offset:96
	v_mul_f32_e32 v154, v73, v147
	v_cvt_pk_bf16_f32 v154, v154, s0
	ds_write_b16 v140, v154 offset:144
	v_mul_f32_e32 v155, v77, v147
	v_cvt_pk_bf16_f32 v155, v155, s0
	ds_write_b16 v140, v155 offset:176
	v_mul_f32_e32 v156, v81, v147
	v_cvt_pk_bf16_f32 v156, v156, s0
	ds_write_b16 v140, v156 offset:208
	v_mul_f32_e32 v157, v85, v147
	v_cvt_pk_bf16_f32 v157, v157, s0
	ds_write_b16 v140, v157 offset:240
	v_mul_f32_e32 v154, v74, v148
	v_cvt_pk_bf16_f32 v154, v154, s0
	ds_write_b16 v140, v154 offset:288
	v_mul_f32_e32 v155, v78, v148
	v_cvt_pk_bf16_f32 v155, v155, s0
	ds_write_b16 v140, v155 offset:320
	v_mul_f32_e32 v156, v82, v148
	v_cvt_pk_bf16_f32 v156, v156, s0
	ds_write_b16 v140, v156 offset:352
	v_mul_f32_e32 v157, v86, v148
	v_cvt_pk_bf16_f32 v157, v157, s0
	ds_write_b16 v140, v157 offset:384
	v_mul_f32_e32 v154, v75, v149
	v_cvt_pk_bf16_f32 v154, v154, s0
	ds_write_b16 v140, v154 offset:432
	v_mul_f32_e32 v155, v79, v149
	v_cvt_pk_bf16_f32 v155, v155, s0
	ds_write_b16 v140, v155 offset:464
	v_mul_f32_e32 v156, v83, v149
	v_cvt_pk_bf16_f32 v156, v156, s0
	ds_write_b16 v140, v156 offset:496
	v_mul_f32_e32 v157, v87, v149
	v_cvt_pk_bf16_f32 v157, v157, s0
	ds_write_b16 v140, v157 offset:528
	s_cbranch_execz .LBB0_1184
